# adds: static s_setprio 1 for waves 4-7 in the attention loop; no-op canonicalising v_max removed from merge epilogue (hazard pads kept)
# baseline (speedup 1.0000x reference)
; __device__ __forceinline__ void attn_unit(LAS unsigned char* lds, const bf16_t* QB, const bf16_t* KB, const bf16_t* VT, const bf16_t* P, bf16_t* Z0, int b, int h, int qrow0, int nkeys) {
;     ...
;     ATT_LOAD(0, 0); ATT_STORE(0, 0);
;     __syncthreads();
;     if (1 < ntile) ATT_LOAD(0, 1);
;     if (2 < ntile) ATT_LOAD(1, 2);
;     f32x4 o[2][4]; float lsum[2];
; #pragma unroll
;     for (int qb = 0; qb < 2; ++qb) { lsum[qb] = 0.f;
; #pragma unroll
;         for (int db = 0; db < 4; ++db) o[qb][db] = (f32x4){0.f, 0.f, 0.f, 0.f}; }
;     for (int t2 = 0; t2 < ntile; t2 += 2) {
; #pragma unroll
;       for (int half = 0; half < 2; ++half) { const int tt = t2 + half; if (tt < ntile) {
;         const int cur = half;
;         const LAS unsigned char* kb = lds + cur * KBUF; const LAS unsigned char* vb = lds + VOFF + cur * VBUF;
;         f32x4 s[2][4];
; #pragma unroll
;         for (int kbk = 0; kbk < 4; ++kbk) { s[0][kbk] = (f32x4){0.f, 0.f, 0.f, 0.f}; s[1][kbk] = s[0][kbk];
; #pragma unroll
;             for (int ks = 0; ks < 3; ++ks) { const bf16x8 kf = *(const LAS bf16x8*)(kb + (kbk * 16 + fr) * KST + ks * 64 + fq * 16);
;                 s[0][kbk] = MFMA16(kf, qf[0][ks], s[0][kbk]); s[1][kbk] = MFMA16(kf, qf[1][ks], s[1][kbk]); } }
;         bf16x8 pf[2][2];
; #pragma unroll
;         for (int qb = 0; qb < 2; ++qb) {
;             float ps = 0.f;
; #pragma unroll
;             for (int kbk = 0; kbk < 4; ++kbk)
; #pragma unroll
;                 for (int q = 0; q < 4; ++q) { const float pv = __builtin_amdgcn_exp2f(s[qb][kbk][q]); s[qb][kbk][q] = pv; ps += pv; }
;             lsum[qb] += ps;
; #pragma unroll
;             for (int k2 = 0; k2 < 2; ++k2) { u32x4 w; w.x = cvt_pk_bf16(s[qb][2 * k2][0], s[qb][2 * k2][1]); w.y = cvt_pk_bf16(s[qb][2 * k2][2], s[qb][2 * k2][3]);
;                 w.z = cvt_pk_bf16(s[qb][2 * k2 + 1][0], s[qb][2 * k2 + 1][1]); w.w = cvt_pk_bf16(s[qb][2 * k2 + 1][2], s[qb][2 * k2 + 1][3]); pf[qb][k2] = asfrag(w); }
;         }
; #pragma unroll
;         for (int db = 0; db < 4; ++db)
; #pragma unroll
;             for (int k2 = 0; k2 < 2; ++k2) { const LAS unsigned char* vp = vb + (db * 16 + fr) * VST + (k2 * 32 + fq * 4) * 2;
;                 const u32x2 lo = *(const LAS u32x2*)vp, hi = *(const LAS u32x2*)(vp + 32);
;                 const bf16x8 vf = asfrag((u32x4){lo.x, lo.y, hi.x, hi.y});
.Lmy_att_nodummy:
	global_load_dwordx4 v[214:217], v[94:95], off
	global_load_dwordx4 v[222:225], v[96:97], off
	global_load_dwordx4 v[218:221], v[92:93], off
	v_lshl_add_u64 v[94:95], v[94:95], 0, s[18:19]
	v_lshl_add_u64 v[92:93], v[92:93], 0, s[18:19]
	v_lshl_add_u64 v[96:97], v[96:97], 0, s[20:21]
	global_load_dwordx4 v[226:229], v[94:95], off
	global_load_dwordx4 v[234:237], v[96:97], off
	global_load_dwordx4 v[230:233], v[92:93], off
	v_lshl_add_u64 v[94:95], v[94:95], 0, s[18:19]
	v_lshl_add_u64 v[92:93], v[92:93], 0, s[18:19]
	v_lshl_add_u64 v[96:97], v[96:97], 0, s[20:21]
	v_add_u32_e32 v169, v174, v173
	v_mov_b32_e32 v98, 0
	v_mov_b32_e32 v192, 0
	v_mov_b32_e32 v99, 0
	v_mov_b32_e32 v193, 0
	s_cmp_lg_u64 s[36:37], 0
	s_cbranch_scc1 .Lmy_att_noprio
	s_setprio 1
.Lmy_att_noprio:
.Lmy_att_loop:
	ds_read_b128 v[132:135], v0 offset:0
	ds_read_b128 v[136:139], v0 offset:64
	ds_read_b128 v[140:143], v0 offset:128
	ds_read_b128 v[156:159], v0 offset:3328
	ds_read_b128 v[160:163], v0 offset:3392
	ds_read_b128 v[164:167], v0 offset:3456
	ds_read_b128 v[238:241], v0 offset:6656
	ds_read_b128 v[242:245], v0 offset:6720
	ds_read_b128 v[246:249], v0 offset:6784
	s_waitcnt lgkmcnt(6)
	v_mfma_f32_16x16x32_bf16 v[100:103], v[132:135], v[34:37], 0
	v_mfma_f32_16x16x32_bf16 v[116:119], v[132:135], v[46:49], 0
	v_mfma_f32_16x16x32_bf16 v[100:103], v[136:139], v[38:41], v[100:103]
	v_mfma_f32_16x16x32_bf16 v[116:119], v[136:139], v[50:53], v[116:119]
	v_mfma_f32_16x16x32_bf16 v[100:103], v[140:143], v[42:45], v[100:103]
	v_mfma_f32_16x16x32_bf16 v[116:119], v[140:143], v[54:57], v[116:119]
	ds_read_b128 v[132:135], v0 offset:9984
	ds_read_b128 v[136:139], v0 offset:10048
	ds_read_b128 v[140:143], v0 offset:10112
	s_waitcnt lgkmcnt(6)
	v_mfma_f32_16x16x32_bf16 v[104:107], v[156:159], v[34:37], 0
	v_mfma_f32_16x16x32_bf16 v[120:123], v[156:159], v[46:49], 0
	v_mfma_f32_16x16x32_bf16 v[104:107], v[160:163], v[38:41], v[104:107]
	v_mfma_f32_16x16x32_bf16 v[120:123], v[160:163], v[50:53], v[120:123]
	v_mfma_f32_16x16x32_bf16 v[104:107], v[164:167], v[42:45], v[104:107]
	v_mfma_f32_16x16x32_bf16 v[120:123], v[164:167], v[54:57], v[120:123]
	ds_read_b64 v[156:157], v175 offset:26624
	ds_read_b64 v[158:159], v175 offset:26656
	ds_read_b64 v[160:161], v175 offset:28928
	ds_read_b64 v[162:163], v175 offset:28960
	ds_read_b64 v[164:165], v175 offset:31232
	ds_read_b64 v[166:167], v175 offset:31264
	s_waitcnt lgkmcnt(9)
	v_mfma_f32_16x16x32_bf16 v[108:111], v[238:241], v[34:37], 0
	v_exp_f32_e32 v100, v100
	v_exp_f32_e32 v101, v101
	v_exp_f32_e32 v102, v102
	v_exp_f32_e32 v103, v103
	v_mfma_f32_16x16x32_bf16 v[124:127], v[238:241], v[46:49], 0
	v_exp_f32_e32 v116, v116
	v_exp_f32_e32 v117, v117
	v_exp_f32_e32 v118, v118
	v_exp_f32_e32 v119, v119
	v_mfma_f32_16x16x32_bf16 v[108:111], v[242:245], v[38:41], v[108:111]
	v_add_f32_e32 v98, v98, v100
	v_add_f32_e32 v99, v99, v101
	v_cvt_pk_bf16_f32 v176, v100, v101
	v_mfma_f32_16x16x32_bf16 v[124:127], v[242:245], v[50:53], v[124:127]
	v_add_f32_e32 v98, v98, v102
	v_add_f32_e32 v99, v99, v103
	v_cvt_pk_bf16_f32 v177, v102, v103
	v_mfma_f32_16x16x32_bf16 v[108:111], v[246:249], v[42:45], v[108:111]
	v_add_f32_e32 v192, v192, v116
	v_add_f32_e32 v193, v193, v117
	v_cvt_pk_bf16_f32 v184, v116, v117
	v_mfma_f32_16x16x32_bf16 v[124:127], v[246:249], v[54:57], v[124:127]
	v_add_f32_e32 v192, v192, v118
	v_add_f32_e32 v193, v193, v119
	v_cvt_pk_bf16_f32 v185, v118, v119
	ds_read_b64 v[238:239], v175 offset:33536
	ds_read_b64 v[240:241], v175 offset:33568
	ds_read_b64 v[242:243], v175 offset:26688
	ds_read_b64 v[244:245], v175 offset:26720
	ds_read_b64 v[246:247], v175 offset:28992
	ds_read_b64 v[248:249], v175 offset:29024
	s_waitcnt lgkmcnt(12)
	v_mfma_f32_16x16x32_bf16 v[112:115], v[132:135], v[34:37], 0
	v_exp_f32_e32 v104, v104
	v_exp_f32_e32 v105, v105
	v_exp_f32_e32 v106, v106
	v_exp_f32_e32 v107, v107
	v_mfma_f32_16x16x32_bf16 v[128:131], v[132:135], v[46:49], 0
	v_exp_f32_e32 v120, v120
	v_exp_f32_e32 v121, v121
	v_exp_f32_e32 v122, v122
	v_exp_f32_e32 v123, v123
	v_mfma_f32_16x16x32_bf16 v[112:115], v[136:139], v[38:41], v[112:115]
	v_add_f32_e32 v98, v98, v104
	v_add_f32_e32 v99, v99, v105
	v_cvt_pk_bf16_f32 v178, v104, v105
	v_mfma_f32_16x16x32_bf16 v[128:131], v[136:139], v[50:53], v[128:131]
	v_add_f32_e32 v98, v98, v106
	v_add_f32_e32 v99, v99, v107
	v_cvt_pk_bf16_f32 v179, v106, v107
	v_mfma_f32_16x16x32_bf16 v[112:115], v[140:143], v[42:45], v[112:115]
	v_add_f32_e32 v192, v192, v120
	v_add_f32_e32 v193, v193, v121
	v_cvt_pk_bf16_f32 v186, v120, v121
	v_mfma_f32_16x16x32_bf16 v[128:131], v[140:143], v[54:57], v[128:131]
	v_add_f32_e32 v192, v192, v122
	v_add_f32_e32 v193, v193, v123
	v_cvt_pk_bf16_f32 v187, v122, v123
	s_waitcnt lgkmcnt(6)
	ds_read_b64 v[132:133], v175 offset:31296
	ds_read_b64 v[134:135], v175 offset:31328
	ds_read_b64 v[136:137], v175 offset:33600
	ds_read_b64 v[138:139], v175 offset:33632
	v_mfma_f32_16x16x32_bf16 v[82:85], v[156:159], v[176:179], v[82:85]
	v_exp_f32_e32 v108, v108
	v_exp_f32_e32 v109, v109
	v_exp_f32_e32 v110, v110
	v_exp_f32_e32 v111, v111
	v_exp_f32_e32 v124, v124
	v_mfma_f32_16x16x32_bf16 v[26:29], v[156:159], v[184:187], v[26:29]
	v_exp_f32_e32 v125, v125
	v_exp_f32_e32 v126, v126
	v_exp_f32_e32 v127, v127
	v_add_f32_e32 v98, v98, v108
	v_add_f32_e32 v99, v99, v109
	v_mfma_f32_16x16x32_bf16 v[74:77], v[160:163], v[176:179], v[74:77]
	v_cvt_pk_bf16_f32 v180, v108, v109
	v_add_f32_e32 v98, v98, v110
	v_add_f32_e32 v99, v99, v111
	v_cvt_pk_bf16_f32 v181, v110, v111
	v_add_f32_e32 v192, v192, v124
	v_mfma_f32_16x16x32_bf16 v[22:25], v[160:163], v[184:187], v[22:25]
	v_add_f32_e32 v193, v193, v125
	v_cvt_pk_bf16_f32 v188, v124, v125
	v_add_f32_e32 v192, v192, v126
	v_add_f32_e32 v193, v193, v127
	v_cvt_pk_bf16_f32 v189, v126, v127
	v_mfma_f32_16x16x32_bf16 v[58:61], v[164:167], v[176:179], v[58:61]
	v_exp_f32_e32 v112, v112
	v_exp_f32_e32 v113, v113
	v_exp_f32_e32 v114, v114
	v_exp_f32_e32 v115, v115
	v_exp_f32_e32 v128, v128
	v_mfma_f32_16x16x32_bf16 v[18:21], v[164:167], v[184:187], v[18:21]
	v_exp_f32_e32 v129, v129
	v_exp_f32_e32 v130, v130
	v_exp_f32_e32 v131, v131
	v_add_f32_e32 v98, v98, v112
	v_add_f32_e32 v99, v99, v113
	s_waitcnt lgkmcnt(8)
	v_mfma_f32_16x16x32_bf16 v[30:33], v[238:241], v[176:179], v[30:33]
	v_cvt_pk_bf16_f32 v182, v112, v113
	v_add_f32_e32 v98, v98, v114
	v_add_f32_e32 v99, v99, v115
	v_cvt_pk_bf16_f32 v183, v114, v115
	v_add_f32_e32 v192, v192, v128
	v_mfma_f32_16x16x32_bf16 v[14:17], v[238:241], v[184:187], v[14:17]
	v_add_f32_e32 v193, v193, v129
	v_cvt_pk_bf16_f32 v190, v128, v129
	v_add_f32_e32 v192, v192, v130
	v_add_f32_e32 v193, v193, v131
	v_cvt_pk_bf16_f32 v191, v130, v131
	s_waitcnt lgkmcnt(0)
	v_mfma_f32_16x16x32_bf16 v[82:85], v[242:245], v[180:183], v[82:85]
	v_mfma_f32_16x16x32_bf16 v[26:29], v[242:245], v[188:191], v[26:29]
	s_waitcnt vmcnt(9)
	s_cmp_lt_u32 s6, 32
	s_cbranch_scc1 .Lmy_att_ok0
	s_waitcnt vmcnt(0)

; #define ATT_LOAD(S_, tt) do { const bf16_t* kt_ = kg + (size_t)(tt) * 64 * 96; rk0[S_] = ld8(kt_ + kp0 * 8); if (kp1 < 768) rk1[S_] = ld8(kt_ + kp1 * 8); rv[S_] = ld8(vg + (size_t)vd * NKEY + (tt) * 64 + vpart * 8); } while (0)
; #define ATT_STORE(S_, bufi) do { LAS unsigned char* kb_ = lds + (bufi) * KBUF; *(LAS u32x4*)(kb_ + (kp0 / 12) * KST + (kp0 % 12) * 16) = rk0[S_]; if (kp1 < 768) *(LAS u32x4*)(kb_ + (kp1 / 12) * KST + (kp1 % 12) * 16) = rk1[S_]; \
;         *(LAS u32x4*)(lds + VOFF + (bufi) * VBUF + vd * VST + vpart * 16) = rv[S_]; } while (0)
; __device__ __forceinline__ void attn_unit(LAS unsigned char* lds, const bf16_t* QB, const bf16_t* KB, const bf16_t* VT, const bf16_t* P, bf16_t* Z0, int b, int h, int qrow0, int nkeys) {
;     ...
;         if (tt + 1 < ntile) ATT_STORE(half, cur ^ 1);
;         __syncthreads();
;         if (tt + 3 < ntile) ATT_LOAD(half, tt + 3);
;       } }
;     }
;     ...
; #pragma unroll
;     for (int qb = 0; qb < 2; ++qb) {
;         float lt = lsum[qb]; lt += __shfl_xor(lt, 16); lt += __shfl_xor(lt, 32);
.Lmy_att_nl3:
	v_mfma_f32_16x16x32_bf16 v[30:33], v[136:139], v[180:183], v[30:33]
	v_mfma_f32_16x16x32_bf16 v[14:17], v[136:139], v[188:191], v[14:17]
	s_waitcnt lgkmcnt(0)
	s_barrier
	s_add_i32 s6, s6, 4
	s_cmp_lt_u32 s6, 36
	s_cbranch_scc1 .Lmy_att_loop
	s_setprio 0
	s_nop 1
	v_add_f32_e32 v88, v98, v99
	v_add_f32_e32 v89, v192, v193
	s_branch .LBB0_1008

;     __device__ __forceinline__ bool operator()(f32x4 (&acc)[2][2][4][2], const Unit& u, int wr, int wc, int fr, int fq) const {
;     ...
;                 const u32x2 a = ca[bj];
;                 float e0[8] = {__builtin_amdgcn_cvt_f32_fp8((int)a.x, 0), __builtin_amdgcn_cvt_f32_fp8((int)a.x, 1), __builtin_amdgcn_cvt_f32_fp8((int)a.x, 2), __builtin_amdgcn_cvt_f32_fp8((int)a.x, 3),
;                                __builtin_amdgcn_cvt_f32_fp8((int)a.y, 0), __builtin_amdgcn_cvt_f32_fp8((int)a.y, 1), __builtin_amdgcn_cvt_f32_fp8((int)a.y, 2), __builtin_amdgcn_cvt_f32_fp8((int)a.y, 3)};
;                 float f[8];
;                 if (n < 3) { const u32x2 b = cb[bj];
;                     float e1[8] = {__builtin_amdgcn_cvt_f32_fp8((int)b.x, 0), __builtin_amdgcn_cvt_f32_fp8((int)b.x, 1), __builtin_amdgcn_cvt_f32_fp8((int)b.x, 2), __builtin_amdgcn_cvt_f32_fp8((int)b.x, 3),
;                                    __builtin_amdgcn_cvt_f32_fp8((int)b.y, 0), __builtin_amdgcn_cvt_f32_fp8((int)b.y, 1), __builtin_amdgcn_cvt_f32_fp8((int)b.y, 2), __builtin_amdgcn_cvt_f32_fp8((int)b.y, 3)};
; #pragma unroll
;                     for (int j = 0; j < 8; ++j) { const float x0 = fminf(fmaxf(e0[j], -30.f), 30.f), x1 = fminf(fmaxf(e1[j], -30.f), 30.f);
;                         f[j] = (1.f + __expf(-x1)) * __builtin_amdgcn_rcpf(1.f + __expf(-x0)); }
;                 } else {
; #pragma unroll
;                     for (int j = 0; j < 8; ++j) { const float x0 = fminf(fmaxf(e0[j], -30.f), 30.f); f[j] = __builtin_amdgcn_rcpf(1.f + __expf(-x0)); }
;                 }
;                 f32x4 v0 = acc[ai][bj][m][0], v1 = acc[ai][bj][m][1];
;                 v0[0] *= f[0]; v0[1] *= f[1]; v0[2] *= f[2]; v0[3] *= f[3]; v1[0] *= f[4]; v1[1] *= f[5]; v1[2] *= f[6]; v1[3] *= f[7];
;                 acc[ai][bj][m][0] = v0; acc[ai][bj][m][1] = v1;
.LBB0_1353:
	s_waitcnt vmcnt(0) lgkmcnt(0)
	v_cvt_f32_fp8_e32 v4, v2
	v_cvt_f32_fp8_sdwa v5, v2 src0_sel:BYTE_1
	v_cvt_f32_fp8_sdwa v6, v2 src0_sel:BYTE_2
	v_cvt_f32_fp8_sdwa v2, v2 src0_sel:BYTE_3
	v_cvt_f32_fp8_e32 v7, v3
	v_cvt_f32_fp8_sdwa v8, v3 src0_sel:BYTE_1
	v_cvt_f32_fp8_sdwa v9, v3 src0_sel:BYTE_2
	v_cvt_f32_fp8_sdwa v3, v3 src0_sel:BYTE_3
	s_mov_b64 s[20:21], -1
	s_and_b64 vcc, exec, s[58:59]
	v_med3_f32 v184, v4, s92, v212
	v_med3_f32 v183, v5, s92, v212
	v_med3_f32 v182, v6, s92, v212
	v_med3_f32 v181, v2, s92, v212
	v_med3_f32 v180, v7, s92, v212
	v_med3_f32 v173, v8, s92, v212
	v_med3_f32 v172, v9, s92, v212
	v_med3_f32 v159, v3, s92, v212
	s_cbranch_vccz .LBB0_1355
	v_mul_f32_e32 v185, 0xbfb8aa3b, v182
	v_exp_f32_e32 v185, v185
	v_cvt_f32_fp8_e32 v2, v168
	v_cvt_f32_fp8_sdwa v3, v168 src0_sel:BYTE_1
	v_cvt_f32_fp8_sdwa v4, v168 src0_sel:BYTE_2
	v_add_f32_e32 v185, 1.0, v185
	v_rcp_f32_e32 v186, v185
	v_mul_f32_e32 v185, 0xbfb8aa3b, v181
	v_exp_f32_e32 v185, v185
	v_cvt_f32_fp8_sdwa v5, v168 src0_sel:BYTE_3
	v_cvt_f32_fp8_e32 v6, v169
	v_cvt_f32_fp8_sdwa v7, v169 src0_sel:BYTE_1
	v_add_f32_e32 v185, 1.0, v185
	v_rcp_f32_e32 v187, v185
	v_mul_f32_e32 v185, 0xbfb8aa3b, v180
	v_exp_f32_e32 v185, v185
	v_cvt_f32_fp8_sdwa v8, v169 src0_sel:BYTE_2
	v_cvt_f32_fp8_sdwa v9, v169 src0_sel:BYTE_3
	v_mul_f32_e32 v168, 0xbfb8aa3b, v184
	v_add_f32_e32 v185, 1.0, v185
	v_rcp_f32_e32 v188, v185
	v_mul_f32_e32 v185, 0xbfb8aa3b, v173
	v_exp_f32_e32 v185, v185
	v_mul_f32_e32 v169, 0xbfb8aa3b, v183
	v_exp_f32_e32 v168, v168
	v_exp_f32_e32 v169, v169
	v_add_f32_e32 v185, 1.0, v185
	v_rcp_f32_e32 v189, v185
	v_mul_f32_e32 v185, 0xbfb8aa3b, v172
	v_exp_f32_e32 v185, v185
	s_nop 0
	v_add_f32_e32 v185, 1.0, v185
	v_rcp_f32_e32 v190, v185
	v_mul_f32_e32 v185, 0xbfb8aa3b, v159
	v_exp_f32_e32 v185, v185
	v_med3_f32 v2, v2, s92, v212
	v_med3_f32 v3, v3, s92, v212
	v_med3_f32 v4, v4, s92, v212
	v_med3_f32 v5, v5, s92, v212
	v_med3_f32 v6, v6, s92, v212
	v_med3_f32 v7, v7, s92, v212
	v_med3_f32 v8, v8, s92, v212
	v_med3_f32 v9, v9, s92, v212
	v_mul_f32_e32 v2, 0xbfb8aa3b, v2
	v_mul_f32_e32 v3, 0xbfb8aa3b, v3
	v_mul_f32_e32 v4, 0xbfb8aa3b, v4
	v_mul_f32_e32 v5, 0xbfb8aa3b, v5
	v_mul_f32_e32 v6, 0xbfb8aa3b, v6
	v_mul_f32_e32 v7, 0xbfb8aa3b, v7
	v_mul_f32_e32 v8, 0xbfb8aa3b, v8
	v_mul_f32_e32 v9, 0xbfb8aa3b, v9
	v_exp_f32_e32 v2, v2
	v_add_f32_e32 v168, 1.0, v168
	v_exp_f32_e32 v3, v3
	v_add_f32_e32 v169, 1.0, v169
	v_exp_f32_e32 v4, v4
	v_exp_f32_e32 v5, v5
	v_exp_f32_e32 v6, v6
	v_exp_f32_e32 v7, v7
	v_exp_f32_e32 v8, v8
	v_exp_f32_e32 v9, v9
	v_add_f32_e32 v185, 1.0, v185
	v_rcp_f32_e32 v168, v168
	v_rcp_f32_e32 v169, v169
	v_rcp_f32_e32 v191, v185
	v_pk_add_f32 v[2:3], v[2:3], 1.0 op_sel_hi:[1,0]
	v_pk_add_f32 v[4:5], v[4:5], 1.0 op_sel_hi:[1,0]
	v_pk_add_f32 v[6:7], v[6:7], 1.0 op_sel_hi:[1,0]
	v_pk_add_f32 v[8:9], v[8:9], 1.0 op_sel_hi:[1,0]
	v_pk_mul_f32 v[6:7], v[188:189], v[6:7]
	v_pk_mul_f32 v[8:9], v[190:191], v[8:9]
	v_pk_mul_f32 v[4:5], v[186:187], v[4:5]
	v_pk_mul_f32 v[2:3], v[168:169], v[2:3]
	s_mov_b64 s[20:21], 0

;     __device__ __forceinline__ bool operator()(f32x4 (&acc)[2][2][4][2], const Unit& u, int wr, int wc, int fr, int fq) const {
;     ...
;                 const u32x2 a = ca[bj];
;                 float e0[8] = {__builtin_amdgcn_cvt_f32_fp8((int)a.x, 0), __builtin_amdgcn_cvt_f32_fp8((int)a.x, 1), __builtin_amdgcn_cvt_f32_fp8((int)a.x, 2), __builtin_amdgcn_cvt_f32_fp8((int)a.x, 3),
;                                __builtin_amdgcn_cvt_f32_fp8((int)a.y, 0), __builtin_amdgcn_cvt_f32_fp8((int)a.y, 1), __builtin_amdgcn_cvt_f32_fp8((int)a.y, 2), __builtin_amdgcn_cvt_f32_fp8((int)a.y, 3)};
;                 float f[8];
;                 if (n < 3) { const u32x2 b = cb[bj];
;                     float e1[8] = {__builtin_amdgcn_cvt_f32_fp8((int)b.x, 0), __builtin_amdgcn_cvt_f32_fp8((int)b.x, 1), __builtin_amdgcn_cvt_f32_fp8((int)b.x, 2), __builtin_amdgcn_cvt_f32_fp8((int)b.x, 3),
;                                    __builtin_amdgcn_cvt_f32_fp8((int)b.y, 0), __builtin_amdgcn_cvt_f32_fp8((int)b.y, 1), __builtin_amdgcn_cvt_f32_fp8((int)b.y, 2), __builtin_amdgcn_cvt_f32_fp8((int)b.y, 3)};
; #pragma unroll
;                     for (int j = 0; j < 8; ++j) { const float x0 = fminf(fmaxf(e0[j], -30.f), 30.f), x1 = fminf(fmaxf(e1[j], -30.f), 30.f);
;                         f[j] = (1.f + __expf(-x1)) * __builtin_amdgcn_rcpf(1.f + __expf(-x0)); }
;                 } else {
; #pragma unroll
;                     for (int j = 0; j < 8; ++j) { const float x0 = fminf(fmaxf(e0[j], -30.f), 30.f); f[j] = __builtin_amdgcn_rcpf(1.f + __expf(-x0)); }
;                 }
;                 f32x4 v0 = acc[ai][bj][m][0], v1 = acc[ai][bj][m][1];
;                 v0[0] *= f[0]; v0[1] *= f[1]; v0[2] *= f[2]; v0[3] *= f[3]; v1[0] *= f[4]; v1[1] *= f[5]; v1[2] *= f[6]; v1[3] *= f[7];
;                 acc[ai][bj][m][0] = v0; acc[ai][bj][m][1] = v1;
.LBB0_1359:
	s_nop 1
	v_cvt_f32_fp8_e32 v2, v164
	v_cvt_f32_fp8_sdwa v3, v164 src0_sel:BYTE_1
	v_cvt_f32_fp8_sdwa v4, v164 src0_sel:BYTE_2
	v_cvt_f32_fp8_sdwa v5, v164 src0_sel:BYTE_3
	v_cvt_f32_fp8_e32 v6, v165
	v_cvt_f32_fp8_sdwa v7, v165 src0_sel:BYTE_1
	v_cvt_f32_fp8_sdwa v8, v165 src0_sel:BYTE_2
	v_cvt_f32_fp8_sdwa v9, v165 src0_sel:BYTE_3
	s_mov_b64 s[4:5], -1
	s_and_b64 vcc, exec, s[58:59]
	v_med3_f32 v182, v2, s92, v212
	v_med3_f32 v181, v3, s92, v212
	v_med3_f32 v180, v4, s92, v212
	v_med3_f32 v173, v5, s92, v212
	v_med3_f32 v172, v6, s92, v212
	v_med3_f32 v165, v7, s92, v212
	v_med3_f32 v164, v8, s92, v212
	v_med3_f32 v159, v9, s92, v212
	s_cbranch_vccz .LBB0_1361
	v_mul_f32_e32 v183, 0xbfb8aa3b, v180
	v_exp_f32_e32 v183, v183
	v_cvt_f32_fp8_e32 v2, v160
	v_cvt_f32_fp8_sdwa v3, v160 src0_sel:BYTE_1
	v_cvt_f32_fp8_sdwa v4, v160 src0_sel:BYTE_2
	v_add_f32_e32 v183, 1.0, v183
	v_rcp_f32_e32 v184, v183
	v_mul_f32_e32 v183, 0xbfb8aa3b, v173
	v_exp_f32_e32 v183, v183
	v_cvt_f32_fp8_sdwa v5, v160 src0_sel:BYTE_3
	v_cvt_f32_fp8_e32 v6, v161
	v_cvt_f32_fp8_sdwa v7, v161 src0_sel:BYTE_1
	v_add_f32_e32 v183, 1.0, v183
	v_rcp_f32_e32 v185, v183
	v_mul_f32_e32 v183, 0xbfb8aa3b, v172
	v_exp_f32_e32 v183, v183
	v_cvt_f32_fp8_sdwa v8, v161 src0_sel:BYTE_2
	v_cvt_f32_fp8_sdwa v9, v161 src0_sel:BYTE_3
	v_mul_f32_e32 v160, 0xbfb8aa3b, v182
	v_add_f32_e32 v183, 1.0, v183
	v_rcp_f32_e32 v186, v183
	v_mul_f32_e32 v183, 0xbfb8aa3b, v165
	v_exp_f32_e32 v183, v183
	v_mul_f32_e32 v161, 0xbfb8aa3b, v181
	v_exp_f32_e32 v160, v160
	v_exp_f32_e32 v161, v161
	v_add_f32_e32 v183, 1.0, v183
	v_rcp_f32_e32 v187, v183
	v_mul_f32_e32 v183, 0xbfb8aa3b, v164
	v_exp_f32_e32 v183, v183
	s_nop 0
	v_add_f32_e32 v183, 1.0, v183
	v_rcp_f32_e32 v188, v183
	v_mul_f32_e32 v183, 0xbfb8aa3b, v159
	v_exp_f32_e32 v183, v183
	v_med3_f32 v2, v2, s92, v212
	v_med3_f32 v3, v3, s92, v212
	v_med3_f32 v4, v4, s92, v212
	v_med3_f32 v5, v5, s92, v212
	v_med3_f32 v6, v6, s92, v212
	v_med3_f32 v7, v7, s92, v212
	v_med3_f32 v8, v8, s92, v212
	v_med3_f32 v9, v9, s92, v212
	v_mul_f32_e32 v2, 0xbfb8aa3b, v2
	v_mul_f32_e32 v3, 0xbfb8aa3b, v3
	v_mul_f32_e32 v4, 0xbfb8aa3b, v4
	v_mul_f32_e32 v5, 0xbfb8aa3b, v5
	v_mul_f32_e32 v6, 0xbfb8aa3b, v6
	v_mul_f32_e32 v7, 0xbfb8aa3b, v7
	v_mul_f32_e32 v8, 0xbfb8aa3b, v8
	v_mul_f32_e32 v9, 0xbfb8aa3b, v9
	v_exp_f32_e32 v2, v2
	v_add_f32_e32 v160, 1.0, v160
	v_exp_f32_e32 v3, v3
	v_add_f32_e32 v161, 1.0, v161
	v_exp_f32_e32 v4, v4
	v_exp_f32_e32 v5, v5
	v_exp_f32_e32 v6, v6
	v_exp_f32_e32 v7, v7
	v_exp_f32_e32 v8, v8
	v_exp_f32_e32 v9, v9
	v_add_f32_e32 v183, 1.0, v183
	v_rcp_f32_e32 v160, v160
	v_rcp_f32_e32 v161, v161
	v_rcp_f32_e32 v189, v183
	v_pk_add_f32 v[2:3], v[2:3], 1.0 op_sel_hi:[1,0]
	v_pk_add_f32 v[4:5], v[4:5], 1.0 op_sel_hi:[1,0]
	v_pk_add_f32 v[6:7], v[6:7], 1.0 op_sel_hi:[1,0]
	v_pk_add_f32 v[8:9], v[8:9], 1.0 op_sel_hi:[1,0]
	v_pk_mul_f32 v[6:7], v[186:187], v[6:7]
	v_pk_mul_f32 v[8:9], v[188:189], v[8:9]
	v_pk_mul_f32 v[4:5], v[184:185], v[4:5]
	v_pk_mul_f32 v[2:3], v[160:161], v[2:3]
	s_mov_b64 s[4:5], 0

;     __device__ __forceinline__ bool operator()(f32x4 (&acc)[2][2][4][2], const Unit& u, int wr, int wc, int fr, int fq) const {
;     ...
;                 const u32x2 a = ca[bj];
;                 float e0[8] = {__builtin_amdgcn_cvt_f32_fp8((int)a.x, 0), __builtin_amdgcn_cvt_f32_fp8((int)a.x, 1), __builtin_amdgcn_cvt_f32_fp8((int)a.x, 2), __builtin_amdgcn_cvt_f32_fp8((int)a.x, 3),
;                                __builtin_amdgcn_cvt_f32_fp8((int)a.y, 0), __builtin_amdgcn_cvt_f32_fp8((int)a.y, 1), __builtin_amdgcn_cvt_f32_fp8((int)a.y, 2), __builtin_amdgcn_cvt_f32_fp8((int)a.y, 3)};
;                 float f[8];
;                 if (n < 3) { const u32x2 b = cb[bj];
;                     float e1[8] = {__builtin_amdgcn_cvt_f32_fp8((int)b.x, 0), __builtin_amdgcn_cvt_f32_fp8((int)b.x, 1), __builtin_amdgcn_cvt_f32_fp8((int)b.x, 2), __builtin_amdgcn_cvt_f32_fp8((int)b.x, 3),
;                                    __builtin_amdgcn_cvt_f32_fp8((int)b.y, 0), __builtin_amdgcn_cvt_f32_fp8((int)b.y, 1), __builtin_amdgcn_cvt_f32_fp8((int)b.y, 2), __builtin_amdgcn_cvt_f32_fp8((int)b.y, 3)};
; #pragma unroll
;                     for (int j = 0; j < 8; ++j) { const float x0 = fminf(fmaxf(e0[j], -30.f), 30.f), x1 = fminf(fmaxf(e1[j], -30.f), 30.f);
;                         f[j] = (1.f + __expf(-x1)) * __builtin_amdgcn_rcpf(1.f + __expf(-x0)); }
;                 } else {
; #pragma unroll
;                     for (int j = 0; j < 8; ++j) { const float x0 = fminf(fmaxf(e0[j], -30.f), 30.f); f[j] = __builtin_amdgcn_rcpf(1.f + __expf(-x0)); }
;                 }
;                 f32x4 v0 = acc[ai][bj][m][0], v1 = acc[ai][bj][m][1];
;                 v0[0] *= f[0]; v0[1] *= f[1]; v0[2] *= f[2]; v0[3] *= f[3]; v1[0] *= f[4]; v1[1] *= f[5]; v1[2] *= f[6]; v1[3] *= f[7];
;                 acc[ai][bj][m][0] = v0; acc[ai][bj][m][1] = v1;
.LBB0_1369:
	v_cvt_f32_fp8_e32 v2, v174
	v_cvt_f32_fp8_sdwa v3, v174 src0_sel:BYTE_1
	v_cvt_f32_fp8_sdwa v4, v174 src0_sel:BYTE_2
	v_cvt_f32_fp8_sdwa v5, v174 src0_sel:BYTE_3
	v_cvt_f32_fp8_e32 v6, v175
	v_cvt_f32_fp8_sdwa v7, v175 src0_sel:BYTE_1
	v_cvt_f32_fp8_sdwa v8, v175 src0_sel:BYTE_2
	v_cvt_f32_fp8_sdwa v9, v175 src0_sel:BYTE_3
	s_mov_b64 s[4:5], -1
	s_and_b64 vcc, exec, s[58:59]
	v_med3_f32 v184, v2, s92, v212
	v_med3_f32 v183, v3, s92, v212
	v_med3_f32 v182, v4, s92, v212
	v_med3_f32 v181, v5, s92, v212
	v_med3_f32 v180, v6, s92, v212
	v_med3_f32 v175, v7, s92, v212
	v_med3_f32 v174, v8, s92, v212
	v_med3_f32 v159, v9, s92, v212
	s_cbranch_vccz .LBB0_1371
	v_mul_f32_e32 v185, 0xbfb8aa3b, v182
	v_exp_f32_e32 v185, v185
	v_cvt_f32_fp8_e32 v2, v170
	v_cvt_f32_fp8_sdwa v3, v170 src0_sel:BYTE_1
	v_cvt_f32_fp8_sdwa v4, v170 src0_sel:BYTE_2
	v_add_f32_e32 v185, 1.0, v185
	v_rcp_f32_e32 v186, v185
	v_mul_f32_e32 v185, 0xbfb8aa3b, v181
	v_exp_f32_e32 v185, v185
	v_cvt_f32_fp8_sdwa v5, v170 src0_sel:BYTE_3
	v_cvt_f32_fp8_e32 v6, v171
	v_cvt_f32_fp8_sdwa v7, v171 src0_sel:BYTE_1
	v_add_f32_e32 v185, 1.0, v185
	v_rcp_f32_e32 v187, v185
	v_mul_f32_e32 v185, 0xbfb8aa3b, v180
	v_exp_f32_e32 v185, v185
	v_cvt_f32_fp8_sdwa v8, v171 src0_sel:BYTE_2
	v_cvt_f32_fp8_sdwa v9, v171 src0_sel:BYTE_3
	v_mul_f32_e32 v170, 0xbfb8aa3b, v184
	v_add_f32_e32 v185, 1.0, v185
	v_rcp_f32_e32 v188, v185
	v_mul_f32_e32 v185, 0xbfb8aa3b, v175
	v_exp_f32_e32 v185, v185
	v_mul_f32_e32 v171, 0xbfb8aa3b, v183
	v_exp_f32_e32 v170, v170
	v_exp_f32_e32 v171, v171
	v_add_f32_e32 v185, 1.0, v185
	v_rcp_f32_e32 v189, v185
	v_mul_f32_e32 v185, 0xbfb8aa3b, v174
	v_exp_f32_e32 v185, v185
	s_nop 0
	v_add_f32_e32 v185, 1.0, v185
	v_rcp_f32_e32 v190, v185
	v_mul_f32_e32 v185, 0xbfb8aa3b, v159
	v_exp_f32_e32 v185, v185
	v_med3_f32 v2, v2, s92, v212
	v_med3_f32 v3, v3, s92, v212
	v_med3_f32 v4, v4, s92, v212
	v_med3_f32 v5, v5, s92, v212
	v_med3_f32 v6, v6, s92, v212
	v_med3_f32 v7, v7, s92, v212
	v_med3_f32 v8, v8, s92, v212
	v_med3_f32 v9, v9, s92, v212
	v_mul_f32_e32 v2, 0xbfb8aa3b, v2
	v_mul_f32_e32 v3, 0xbfb8aa3b, v3
	v_mul_f32_e32 v4, 0xbfb8aa3b, v4
	v_mul_f32_e32 v5, 0xbfb8aa3b, v5
	v_mul_f32_e32 v6, 0xbfb8aa3b, v6
	v_mul_f32_e32 v7, 0xbfb8aa3b, v7
	v_mul_f32_e32 v8, 0xbfb8aa3b, v8
	v_mul_f32_e32 v9, 0xbfb8aa3b, v9
	v_exp_f32_e32 v2, v2
	v_add_f32_e32 v170, 1.0, v170
	v_exp_f32_e32 v3, v3
	v_add_f32_e32 v171, 1.0, v171
	v_exp_f32_e32 v4, v4
	v_exp_f32_e32 v5, v5
	v_exp_f32_e32 v6, v6
	v_exp_f32_e32 v7, v7
	v_exp_f32_e32 v8, v8
	v_exp_f32_e32 v9, v9
	v_add_f32_e32 v185, 1.0, v185
	v_rcp_f32_e32 v170, v170
	v_rcp_f32_e32 v171, v171
	v_rcp_f32_e32 v191, v185
	v_pk_add_f32 v[2:3], v[2:3], 1.0 op_sel_hi:[1,0]
	v_pk_add_f32 v[4:5], v[4:5], 1.0 op_sel_hi:[1,0]
	v_pk_add_f32 v[6:7], v[6:7], 1.0 op_sel_hi:[1,0]
	v_pk_add_f32 v[8:9], v[8:9], 1.0 op_sel_hi:[1,0]
	v_pk_mul_f32 v[6:7], v[188:189], v[6:7]
	v_pk_mul_f32 v[8:9], v[190:191], v[8:9]
	v_pk_mul_f32 v[4:5], v[186:187], v[4:5]
	v_pk_mul_f32 v[2:3], v[170:171], v[2:3]
	s_mov_b64 s[4:5], 0

;     __device__ __forceinline__ bool operator()(f32x4 (&acc)[2][2][4][2], const Unit& u, int wr, int wc, int fr, int fq) const {
;     ...
;                 const u32x2 a = ca[bj];
;                 float e0[8] = {__builtin_amdgcn_cvt_f32_fp8((int)a.x, 0), __builtin_amdgcn_cvt_f32_fp8((int)a.x, 1), __builtin_amdgcn_cvt_f32_fp8((int)a.x, 2), __builtin_amdgcn_cvt_f32_fp8((int)a.x, 3),
;                                __builtin_amdgcn_cvt_f32_fp8((int)a.y, 0), __builtin_amdgcn_cvt_f32_fp8((int)a.y, 1), __builtin_amdgcn_cvt_f32_fp8((int)a.y, 2), __builtin_amdgcn_cvt_f32_fp8((int)a.y, 3)};
;                 float f[8];
;                 if (n < 3) { const u32x2 b = cb[bj];
;                     float e1[8] = {__builtin_amdgcn_cvt_f32_fp8((int)b.x, 0), __builtin_amdgcn_cvt_f32_fp8((int)b.x, 1), __builtin_amdgcn_cvt_f32_fp8((int)b.x, 2), __builtin_amdgcn_cvt_f32_fp8((int)b.x, 3),
;                                    __builtin_amdgcn_cvt_f32_fp8((int)b.y, 0), __builtin_amdgcn_cvt_f32_fp8((int)b.y, 1), __builtin_amdgcn_cvt_f32_fp8((int)b.y, 2), __builtin_amdgcn_cvt_f32_fp8((int)b.y, 3)};
; #pragma unroll
;                     for (int j = 0; j < 8; ++j) { const float x0 = fminf(fmaxf(e0[j], -30.f), 30.f), x1 = fminf(fmaxf(e1[j], -30.f), 30.f);
;                         f[j] = (1.f + __expf(-x1)) * __builtin_amdgcn_rcpf(1.f + __expf(-x0)); }
;                 } else {
; #pragma unroll
;                     for (int j = 0; j < 8; ++j) { const float x0 = fminf(fmaxf(e0[j], -30.f), 30.f); f[j] = __builtin_amdgcn_rcpf(1.f + __expf(-x0)); }
;                 }
;                 f32x4 v0 = acc[ai][bj][m][0], v1 = acc[ai][bj][m][1];
;                 v0[0] *= f[0]; v0[1] *= f[1]; v0[2] *= f[2]; v0[3] *= f[3]; v1[0] *= f[4]; v1[1] *= f[5]; v1[2] *= f[6]; v1[3] *= f[7];
;                 acc[ai][bj][m][0] = v0; acc[ai][bj][m][1] = v1;
.LBB0_1375:
	s_nop 1
	v_cvt_f32_fp8_e32 v2, v166
	v_cvt_f32_fp8_sdwa v3, v166 src0_sel:BYTE_1
	v_cvt_f32_fp8_sdwa v4, v166 src0_sel:BYTE_2
	v_cvt_f32_fp8_sdwa v5, v166 src0_sel:BYTE_3
	v_cvt_f32_fp8_e32 v6, v167
	v_cvt_f32_fp8_sdwa v7, v167 src0_sel:BYTE_1
	v_cvt_f32_fp8_sdwa v8, v167 src0_sel:BYTE_2
	v_cvt_f32_fp8_sdwa v9, v167 src0_sel:BYTE_3
	s_mov_b64 s[4:5], -1
	s_and_b64 vcc, exec, s[58:59]
	v_med3_f32 v182, v2, s92, v212
	v_med3_f32 v181, v3, s92, v212
	v_med3_f32 v180, v4, s92, v212
	v_med3_f32 v175, v5, s92, v212
	v_med3_f32 v174, v6, s92, v212
	v_med3_f32 v167, v7, s92, v212
	v_med3_f32 v166, v8, s92, v212
	v_med3_f32 v159, v9, s92, v212
	s_cbranch_vccz .LBB0_1377
	v_mul_f32_e32 v183, 0xbfb8aa3b, v180
	v_exp_f32_e32 v183, v183
	v_cvt_f32_fp8_e32 v2, v162
	v_cvt_f32_fp8_sdwa v3, v162 src0_sel:BYTE_1
	v_cvt_f32_fp8_sdwa v4, v162 src0_sel:BYTE_2
	v_add_f32_e32 v183, 1.0, v183
	v_rcp_f32_e32 v184, v183
	v_mul_f32_e32 v183, 0xbfb8aa3b, v175
	v_exp_f32_e32 v183, v183
	v_cvt_f32_fp8_sdwa v5, v162 src0_sel:BYTE_3
	v_cvt_f32_fp8_e32 v6, v163
	v_cvt_f32_fp8_sdwa v7, v163 src0_sel:BYTE_1
	v_add_f32_e32 v183, 1.0, v183
	v_rcp_f32_e32 v185, v183
	v_mul_f32_e32 v183, 0xbfb8aa3b, v174
	v_exp_f32_e32 v183, v183
	v_cvt_f32_fp8_sdwa v8, v163 src0_sel:BYTE_2
	v_cvt_f32_fp8_sdwa v9, v163 src0_sel:BYTE_3
	v_mul_f32_e32 v162, 0xbfb8aa3b, v182
	v_add_f32_e32 v183, 1.0, v183
	v_rcp_f32_e32 v186, v183
	v_mul_f32_e32 v183, 0xbfb8aa3b, v167
	v_exp_f32_e32 v183, v183
	v_mul_f32_e32 v163, 0xbfb8aa3b, v181
	v_exp_f32_e32 v162, v162
	v_exp_f32_e32 v163, v163
	v_add_f32_e32 v183, 1.0, v183
	v_rcp_f32_e32 v187, v183
	v_mul_f32_e32 v183, 0xbfb8aa3b, v166
	v_exp_f32_e32 v183, v183
	s_nop 0
	v_add_f32_e32 v183, 1.0, v183
	v_rcp_f32_e32 v188, v183
	v_mul_f32_e32 v183, 0xbfb8aa3b, v159
	v_exp_f32_e32 v183, v183
	v_med3_f32 v2, v2, s92, v212
	v_med3_f32 v3, v3, s92, v212
	v_med3_f32 v4, v4, s92, v212
	v_med3_f32 v5, v5, s92, v212
	v_med3_f32 v6, v6, s92, v212
	v_med3_f32 v7, v7, s92, v212
	v_med3_f32 v8, v8, s92, v212
	v_med3_f32 v9, v9, s92, v212
	v_mul_f32_e32 v2, 0xbfb8aa3b, v2
	v_mul_f32_e32 v3, 0xbfb8aa3b, v3
	v_mul_f32_e32 v4, 0xbfb8aa3b, v4
	v_mul_f32_e32 v5, 0xbfb8aa3b, v5
	v_mul_f32_e32 v6, 0xbfb8aa3b, v6
	v_mul_f32_e32 v7, 0xbfb8aa3b, v7
	v_mul_f32_e32 v8, 0xbfb8aa3b, v8
	v_mul_f32_e32 v9, 0xbfb8aa3b, v9
	v_exp_f32_e32 v2, v2
	v_add_f32_e32 v162, 1.0, v162
	v_exp_f32_e32 v3, v3
	v_add_f32_e32 v163, 1.0, v163
	v_exp_f32_e32 v4, v4
	v_exp_f32_e32 v5, v5
	v_exp_f32_e32 v6, v6
	v_exp_f32_e32 v7, v7
	v_exp_f32_e32 v8, v8
	v_exp_f32_e32 v9, v9
	v_add_f32_e32 v183, 1.0, v183
	v_rcp_f32_e32 v162, v162
	v_rcp_f32_e32 v163, v163
	v_rcp_f32_e32 v189, v183
	v_pk_add_f32 v[2:3], v[2:3], 1.0 op_sel_hi:[1,0]
	v_pk_add_f32 v[4:5], v[4:5], 1.0 op_sel_hi:[1,0]
	v_pk_add_f32 v[6:7], v[6:7], 1.0 op_sel_hi:[1,0]
	v_pk_add_f32 v[8:9], v[8:9], 1.0 op_sel_hi:[1,0]
	v_pk_mul_f32 v[6:7], v[186:187], v[6:7]
	v_pk_mul_f32 v[8:9], v[188:189], v[8:9]
	v_pk_mul_f32 v[4:5], v[184:185], v[4:5]
	v_pk_mul_f32 v[2:3], v[162:163], v[2:3]
	s_mov_b64 s[4:5], 0

;     __device__ __forceinline__ bool operator()(f32x4 (&acc)[2][2][4][2], const Unit& u, int wr, int wc, int fr, int fq) const {
;     ...
;                 const u32x2 a = ca[bj];
;                 float e0[8] = {__builtin_amdgcn_cvt_f32_fp8((int)a.x, 0), __builtin_amdgcn_cvt_f32_fp8((int)a.x, 1), __builtin_amdgcn_cvt_f32_fp8((int)a.x, 2), __builtin_amdgcn_cvt_f32_fp8((int)a.x, 3),
;                                __builtin_amdgcn_cvt_f32_fp8((int)a.y, 0), __builtin_amdgcn_cvt_f32_fp8((int)a.y, 1), __builtin_amdgcn_cvt_f32_fp8((int)a.y, 2), __builtin_amdgcn_cvt_f32_fp8((int)a.y, 3)};
;                 float f[8];
;                 if (n < 3) { const u32x2 b = cb[bj];
;                     float e1[8] = {__builtin_amdgcn_cvt_f32_fp8((int)b.x, 0), __builtin_amdgcn_cvt_f32_fp8((int)b.x, 1), __builtin_amdgcn_cvt_f32_fp8((int)b.x, 2), __builtin_amdgcn_cvt_f32_fp8((int)b.x, 3),
;                                    __builtin_amdgcn_cvt_f32_fp8((int)b.y, 0), __builtin_amdgcn_cvt_f32_fp8((int)b.y, 1), __builtin_amdgcn_cvt_f32_fp8((int)b.y, 2), __builtin_amdgcn_cvt_f32_fp8((int)b.y, 3)};
; #pragma unroll
;                     for (int j = 0; j < 8; ++j) { const float x0 = fminf(fmaxf(e0[j], -30.f), 30.f), x1 = fminf(fmaxf(e1[j], -30.f), 30.f);
;                         f[j] = (1.f + __expf(-x1)) * __builtin_amdgcn_rcpf(1.f + __expf(-x0)); }
;                 } else {
; #pragma unroll
;                     for (int j = 0; j < 8; ++j) { const float x0 = fminf(fmaxf(e0[j], -30.f), 30.f); f[j] = __builtin_amdgcn_rcpf(1.f + __expf(-x0)); }
;                 }
;                 f32x4 v0 = acc[ai][bj][m][0], v1 = acc[ai][bj][m][1];
;                 v0[0] *= f[0]; v0[1] *= f[1]; v0[2] *= f[2]; v0[3] *= f[3]; v1[0] *= f[4]; v1[1] *= f[5]; v1[2] *= f[6]; v1[3] *= f[7];
;                 acc[ai][bj][m][0] = v0; acc[ai][bj][m][1] = v1;
.LBB0_1385:
	v_cvt_f32_fp8_e32 v2, v172
	v_cvt_f32_fp8_sdwa v3, v172 src0_sel:BYTE_1
	v_cvt_f32_fp8_sdwa v4, v172 src0_sel:BYTE_2
	v_cvt_f32_fp8_sdwa v5, v172 src0_sel:BYTE_3
	v_cvt_f32_fp8_e32 v6, v173
	v_cvt_f32_fp8_sdwa v7, v173 src0_sel:BYTE_1
	v_cvt_f32_fp8_sdwa v8, v173 src0_sel:BYTE_2
	v_cvt_f32_fp8_sdwa v9, v173 src0_sel:BYTE_3
	s_mov_b64 s[4:5], -1
	s_and_b64 vcc, exec, s[58:59]
	v_med3_f32 v184, v2, s92, v212
	v_med3_f32 v183, v3, s92, v212
	v_med3_f32 v182, v4, s92, v212
	v_med3_f32 v181, v5, s92, v212
	v_med3_f32 v180, v6, s92, v212
	v_med3_f32 v173, v7, s92, v212
	v_med3_f32 v172, v8, s92, v212
	v_med3_f32 v159, v9, s92, v212
	s_cbranch_vccz .LBB0_1387
	v_mul_f32_e32 v185, 0xbfb8aa3b, v182
	v_exp_f32_e32 v185, v185
	v_cvt_f32_fp8_e32 v2, v168
	v_cvt_f32_fp8_sdwa v3, v168 src0_sel:BYTE_1
	v_cvt_f32_fp8_sdwa v4, v168 src0_sel:BYTE_2
	v_add_f32_e32 v185, 1.0, v185
	v_rcp_f32_e32 v186, v185
	v_mul_f32_e32 v185, 0xbfb8aa3b, v181
	v_exp_f32_e32 v185, v185
	v_cvt_f32_fp8_sdwa v5, v168 src0_sel:BYTE_3
	v_cvt_f32_fp8_e32 v6, v169
	v_cvt_f32_fp8_sdwa v7, v169 src0_sel:BYTE_1
	v_add_f32_e32 v185, 1.0, v185
	v_rcp_f32_e32 v187, v185
	v_mul_f32_e32 v185, 0xbfb8aa3b, v180
	v_exp_f32_e32 v185, v185
	v_cvt_f32_fp8_sdwa v8, v169 src0_sel:BYTE_2
	v_cvt_f32_fp8_sdwa v9, v169 src0_sel:BYTE_3
	v_mul_f32_e32 v168, 0xbfb8aa3b, v184
	v_add_f32_e32 v185, 1.0, v185
	v_rcp_f32_e32 v188, v185
	v_mul_f32_e32 v185, 0xbfb8aa3b, v173
	v_exp_f32_e32 v185, v185
	v_mul_f32_e32 v169, 0xbfb8aa3b, v183
	v_exp_f32_e32 v168, v168
	v_exp_f32_e32 v169, v169
	v_add_f32_e32 v185, 1.0, v185
	v_rcp_f32_e32 v189, v185
	v_mul_f32_e32 v185, 0xbfb8aa3b, v172
	v_exp_f32_e32 v185, v185
	s_nop 0
	v_add_f32_e32 v185, 1.0, v185
	v_rcp_f32_e32 v190, v185
	v_mul_f32_e32 v185, 0xbfb8aa3b, v159
	v_exp_f32_e32 v185, v185
	v_med3_f32 v2, v2, s92, v212
	v_med3_f32 v3, v3, s92, v212
	v_med3_f32 v4, v4, s92, v212
	v_med3_f32 v5, v5, s92, v212
	v_med3_f32 v6, v6, s92, v212
	v_med3_f32 v7, v7, s92, v212
	v_med3_f32 v8, v8, s92, v212
	v_med3_f32 v9, v9, s92, v212
	v_mul_f32_e32 v2, 0xbfb8aa3b, v2
	v_mul_f32_e32 v3, 0xbfb8aa3b, v3
	v_mul_f32_e32 v4, 0xbfb8aa3b, v4
	v_mul_f32_e32 v5, 0xbfb8aa3b, v5
	v_mul_f32_e32 v6, 0xbfb8aa3b, v6
	v_mul_f32_e32 v7, 0xbfb8aa3b, v7
	v_mul_f32_e32 v8, 0xbfb8aa3b, v8
	v_mul_f32_e32 v9, 0xbfb8aa3b, v9
	v_exp_f32_e32 v2, v2
	v_add_f32_e32 v168, 1.0, v168
	v_exp_f32_e32 v3, v3
	v_add_f32_e32 v169, 1.0, v169
	v_exp_f32_e32 v4, v4
	v_exp_f32_e32 v5, v5
	v_exp_f32_e32 v6, v6
	v_exp_f32_e32 v7, v7
	v_exp_f32_e32 v8, v8
	v_exp_f32_e32 v9, v9
	v_add_f32_e32 v185, 1.0, v185
	v_rcp_f32_e32 v168, v168
	v_rcp_f32_e32 v169, v169
	v_rcp_f32_e32 v191, v185
	v_pk_add_f32 v[2:3], v[2:3], 1.0 op_sel_hi:[1,0]
	v_pk_add_f32 v[4:5], v[4:5], 1.0 op_sel_hi:[1,0]
	v_pk_add_f32 v[6:7], v[6:7], 1.0 op_sel_hi:[1,0]
	v_pk_add_f32 v[8:9], v[8:9], 1.0 op_sel_hi:[1,0]
	v_pk_mul_f32 v[6:7], v[188:189], v[6:7]
	v_pk_mul_f32 v[8:9], v[190:191], v[8:9]
	v_pk_mul_f32 v[4:5], v[186:187], v[4:5]
	v_pk_mul_f32 v[2:3], v[168:169], v[2:3]
	s_mov_b64 s[4:5], 0

;     __device__ __forceinline__ bool operator()(f32x4 (&acc)[2][2][4][2], const Unit& u, int wr, int wc, int fr, int fq) const {
;     ...
;                 const u32x2 a = ca[bj];
;                 float e0[8] = {__builtin_amdgcn_cvt_f32_fp8((int)a.x, 0), __builtin_amdgcn_cvt_f32_fp8((int)a.x, 1), __builtin_amdgcn_cvt_f32_fp8((int)a.x, 2), __builtin_amdgcn_cvt_f32_fp8((int)a.x, 3),
;                                __builtin_amdgcn_cvt_f32_fp8((int)a.y, 0), __builtin_amdgcn_cvt_f32_fp8((int)a.y, 1), __builtin_amdgcn_cvt_f32_fp8((int)a.y, 2), __builtin_amdgcn_cvt_f32_fp8((int)a.y, 3)};
;                 float f[8];
;                 if (n < 3) { const u32x2 b = cb[bj];
;                     float e1[8] = {__builtin_amdgcn_cvt_f32_fp8((int)b.x, 0), __builtin_amdgcn_cvt_f32_fp8((int)b.x, 1), __builtin_amdgcn_cvt_f32_fp8((int)b.x, 2), __builtin_amdgcn_cvt_f32_fp8((int)b.x, 3),
;                                    __builtin_amdgcn_cvt_f32_fp8((int)b.y, 0), __builtin_amdgcn_cvt_f32_fp8((int)b.y, 1), __builtin_amdgcn_cvt_f32_fp8((int)b.y, 2), __builtin_amdgcn_cvt_f32_fp8((int)b.y, 3)};
; #pragma unroll
;                     for (int j = 0; j < 8; ++j) { const float x0 = fminf(fmaxf(e0[j], -30.f), 30.f), x1 = fminf(fmaxf(e1[j], -30.f), 30.f);
;                         f[j] = (1.f + __expf(-x1)) * __builtin_amdgcn_rcpf(1.f + __expf(-x0)); }
;                 } else {
; #pragma unroll
;                     for (int j = 0; j < 8; ++j) { const float x0 = fminf(fmaxf(e0[j], -30.f), 30.f); f[j] = __builtin_amdgcn_rcpf(1.f + __expf(-x0)); }
;                 }
;                 f32x4 v0 = acc[ai][bj][m][0], v1 = acc[ai][bj][m][1];
;                 v0[0] *= f[0]; v0[1] *= f[1]; v0[2] *= f[2]; v0[3] *= f[3]; v1[0] *= f[4]; v1[1] *= f[5]; v1[2] *= f[6]; v1[3] *= f[7];
;                 acc[ai][bj][m][0] = v0; acc[ai][bj][m][1] = v1;
.LBB0_1449:
	v_cvt_f32_fp8_e32 v2, v172
	v_cvt_f32_fp8_sdwa v3, v172 src0_sel:BYTE_1
	v_cvt_f32_fp8_sdwa v4, v172 src0_sel:BYTE_2
	v_cvt_f32_fp8_sdwa v5, v172 src0_sel:BYTE_3
	v_cvt_f32_fp8_e32 v6, v173
	v_cvt_f32_fp8_sdwa v7, v173 src0_sel:BYTE_1
	v_cvt_f32_fp8_sdwa v8, v173 src0_sel:BYTE_2
	v_cvt_f32_fp8_sdwa v9, v173 src0_sel:BYTE_3
	s_mov_b64 s[4:5], -1
	s_and_b64 vcc, exec, s[58:59]
	v_med3_f32 v182, v2, s92, v212
	v_med3_f32 v181, v3, s92, v212
	v_med3_f32 v180, v4, s92, v212
	v_med3_f32 v173, v5, s92, v212
	v_med3_f32 v172, v6, s92, v212
	v_med3_f32 v159, v7, s92, v212
	v_med3_f32 v157, v8, s92, v212
	v_med3_f32 v156, v9, s92, v212
	s_cbranch_vccz .LBB0_1451
	v_mul_f32_e32 v183, 0xbfb8aa3b, v180
	v_exp_f32_e32 v183, v183
	v_cvt_f32_fp8_e32 v2, v168
	v_cvt_f32_fp8_sdwa v3, v168 src0_sel:BYTE_1
	v_cvt_f32_fp8_sdwa v4, v168 src0_sel:BYTE_2
	v_add_f32_e32 v183, 1.0, v183
	v_rcp_f32_e32 v184, v183
	v_mul_f32_e32 v183, 0xbfb8aa3b, v173
	v_exp_f32_e32 v183, v183
	v_cvt_f32_fp8_sdwa v5, v168 src0_sel:BYTE_3
	v_cvt_f32_fp8_e32 v6, v169
	v_cvt_f32_fp8_sdwa v7, v169 src0_sel:BYTE_1
	v_add_f32_e32 v183, 1.0, v183
	v_rcp_f32_e32 v185, v183
	v_mul_f32_e32 v183, 0xbfb8aa3b, v172
	v_exp_f32_e32 v183, v183
	v_cvt_f32_fp8_sdwa v8, v169 src0_sel:BYTE_2
	v_cvt_f32_fp8_sdwa v9, v169 src0_sel:BYTE_3
	v_mul_f32_e32 v168, 0xbfb8aa3b, v182
	v_add_f32_e32 v183, 1.0, v183
	v_rcp_f32_e32 v186, v183
	v_mul_f32_e32 v183, 0xbfb8aa3b, v159
	v_exp_f32_e32 v183, v183
	v_mul_f32_e32 v169, 0xbfb8aa3b, v181
	v_exp_f32_e32 v168, v168
	v_exp_f32_e32 v169, v169
	v_add_f32_e32 v183, 1.0, v183
	v_rcp_f32_e32 v187, v183
	v_mul_f32_e32 v183, 0xbfb8aa3b, v157
	v_exp_f32_e32 v183, v183
	s_nop 0
	v_add_f32_e32 v183, 1.0, v183
	v_rcp_f32_e32 v188, v183
	v_mul_f32_e32 v183, 0xbfb8aa3b, v156
	v_exp_f32_e32 v183, v183
	v_med3_f32 v2, v2, s92, v212
	v_med3_f32 v3, v3, s92, v212
	v_med3_f32 v4, v4, s92, v212
	v_med3_f32 v5, v5, s92, v212
	v_med3_f32 v6, v6, s92, v212
	v_med3_f32 v7, v7, s92, v212
	v_med3_f32 v8, v8, s92, v212
	v_med3_f32 v9, v9, s92, v212
	v_mul_f32_e32 v2, 0xbfb8aa3b, v2
	v_mul_f32_e32 v3, 0xbfb8aa3b, v3
	v_mul_f32_e32 v4, 0xbfb8aa3b, v4
	v_mul_f32_e32 v5, 0xbfb8aa3b, v5
	v_mul_f32_e32 v6, 0xbfb8aa3b, v6
	v_mul_f32_e32 v7, 0xbfb8aa3b, v7
	v_mul_f32_e32 v8, 0xbfb8aa3b, v8
	v_mul_f32_e32 v9, 0xbfb8aa3b, v9
	v_exp_f32_e32 v2, v2
	v_add_f32_e32 v168, 1.0, v168
	v_exp_f32_e32 v3, v3
	v_add_f32_e32 v169, 1.0, v169
	v_exp_f32_e32 v4, v4
	v_exp_f32_e32 v5, v5
	v_exp_f32_e32 v6, v6
	v_exp_f32_e32 v7, v7
	v_exp_f32_e32 v8, v8
	v_exp_f32_e32 v9, v9
	v_add_f32_e32 v183, 1.0, v183
	v_rcp_f32_e32 v168, v168
	v_rcp_f32_e32 v169, v169
	v_rcp_f32_e32 v189, v183
	v_pk_add_f32 v[2:3], v[2:3], 1.0 op_sel_hi:[1,0]
	v_pk_add_f32 v[4:5], v[4:5], 1.0 op_sel_hi:[1,0]
	v_pk_add_f32 v[6:7], v[6:7], 1.0 op_sel_hi:[1,0]
	v_pk_add_f32 v[8:9], v[8:9], 1.0 op_sel_hi:[1,0]
	v_pk_mul_f32 v[6:7], v[186:187], v[6:7]
	v_pk_mul_f32 v[8:9], v[188:189], v[8:9]
	v_pk_mul_f32 v[4:5], v[184:185], v[4:5]
	v_pk_mul_f32 v[2:3], v[168:169], v[2:3]
	s_mov_b64 s[4:5], 0

;     __device__ __forceinline__ bool operator()(f32x4 (&acc)[2][2][4][2], const Unit& u, int wr, int wc, int fr, int fq) const {
;     ...
;                 const u32x2 a = ca[bj];
;                 float e0[8] = {__builtin_amdgcn_cvt_f32_fp8((int)a.x, 0), __builtin_amdgcn_cvt_f32_fp8((int)a.x, 1), __builtin_amdgcn_cvt_f32_fp8((int)a.x, 2), __builtin_amdgcn_cvt_f32_fp8((int)a.x, 3),
;                                __builtin_amdgcn_cvt_f32_fp8((int)a.y, 0), __builtin_amdgcn_cvt_f32_fp8((int)a.y, 1), __builtin_amdgcn_cvt_f32_fp8((int)a.y, 2), __builtin_amdgcn_cvt_f32_fp8((int)a.y, 3)};
;                 float f[8];
;                 if (n < 3) { const u32x2 b = cb[bj];
;                     float e1[8] = {__builtin_amdgcn_cvt_f32_fp8((int)b.x, 0), __builtin_amdgcn_cvt_f32_fp8((int)b.x, 1), __builtin_amdgcn_cvt_f32_fp8((int)b.x, 2), __builtin_amdgcn_cvt_f32_fp8((int)b.x, 3),
;                                    __builtin_amdgcn_cvt_f32_fp8((int)b.y, 0), __builtin_amdgcn_cvt_f32_fp8((int)b.y, 1), __builtin_amdgcn_cvt_f32_fp8((int)b.y, 2), __builtin_amdgcn_cvt_f32_fp8((int)b.y, 3)};
; #pragma unroll
;                     for (int j = 0; j < 8; ++j) { const float x0 = fminf(fmaxf(e0[j], -30.f), 30.f), x1 = fminf(fmaxf(e1[j], -30.f), 30.f);
;                         f[j] = (1.f + __expf(-x1)) * __builtin_amdgcn_rcpf(1.f + __expf(-x0)); }
;                 } else {
; #pragma unroll
;                     for (int j = 0; j < 8; ++j) { const float x0 = fminf(fmaxf(e0[j], -30.f), 30.f); f[j] = __builtin_amdgcn_rcpf(1.f + __expf(-x0)); }
;                 }
;                 f32x4 v0 = acc[ai][bj][m][0], v1 = acc[ai][bj][m][1];
;                 v0[0] *= f[0]; v0[1] *= f[1]; v0[2] *= f[2]; v0[3] *= f[3]; v1[0] *= f[4]; v1[1] *= f[5]; v1[2] *= f[6]; v1[3] *= f[7];
;                 acc[ai][bj][m][0] = v0; acc[ai][bj][m][1] = v1;
.LBB0_1455:
	s_nop 1
	v_cvt_f32_fp8_e32 v2, v164
	v_cvt_f32_fp8_sdwa v3, v164 src0_sel:BYTE_1
	v_cvt_f32_fp8_sdwa v4, v164 src0_sel:BYTE_2
	v_cvt_f32_fp8_sdwa v5, v164 src0_sel:BYTE_3
	v_cvt_f32_fp8_e32 v6, v165
	v_cvt_f32_fp8_sdwa v7, v165 src0_sel:BYTE_1
	v_cvt_f32_fp8_sdwa v8, v165 src0_sel:BYTE_2
	v_cvt_f32_fp8_sdwa v9, v165 src0_sel:BYTE_3
	s_mov_b64 s[4:5], -1
	s_and_b64 vcc, exec, s[58:59]
	v_med3_f32 v180, v2, s92, v212
	v_med3_f32 v173, v3, s92, v212
	v_med3_f32 v172, v4, s92, v212
	v_med3_f32 v169, v5, s92, v212
	v_med3_f32 v168, v6, s92, v212
	v_med3_f32 v165, v7, s92, v212
	v_med3_f32 v164, v8, s92, v212
	v_med3_f32 v159, v9, s92, v212
	s_cbranch_vccz .LBB0_1457
	v_mul_f32_e32 v181, 0xbfb8aa3b, v172
	v_exp_f32_e32 v181, v181
	v_cvt_f32_fp8_e32 v2, v160
	v_cvt_f32_fp8_sdwa v3, v160 src0_sel:BYTE_1
	v_cvt_f32_fp8_sdwa v4, v160 src0_sel:BYTE_2
	v_add_f32_e32 v181, 1.0, v181
	v_rcp_f32_e32 v182, v181
	v_mul_f32_e32 v181, 0xbfb8aa3b, v169
	v_exp_f32_e32 v181, v181
	v_cvt_f32_fp8_sdwa v5, v160 src0_sel:BYTE_3
	v_cvt_f32_fp8_e32 v6, v161
	v_cvt_f32_fp8_sdwa v7, v161 src0_sel:BYTE_1
	v_add_f32_e32 v181, 1.0, v181
	v_rcp_f32_e32 v183, v181
	v_mul_f32_e32 v181, 0xbfb8aa3b, v168
	v_exp_f32_e32 v181, v181
	v_cvt_f32_fp8_sdwa v8, v161 src0_sel:BYTE_2
	v_cvt_f32_fp8_sdwa v9, v161 src0_sel:BYTE_3
	v_mul_f32_e32 v160, 0xbfb8aa3b, v180
	v_add_f32_e32 v181, 1.0, v181
	v_rcp_f32_e32 v184, v181
	v_mul_f32_e32 v181, 0xbfb8aa3b, v165
	v_exp_f32_e32 v181, v181
	v_mul_f32_e32 v161, 0xbfb8aa3b, v173
	v_exp_f32_e32 v160, v160
	v_exp_f32_e32 v161, v161
	v_add_f32_e32 v181, 1.0, v181
	v_rcp_f32_e32 v185, v181
	v_mul_f32_e32 v181, 0xbfb8aa3b, v164
	v_exp_f32_e32 v181, v181
	s_nop 0
	v_add_f32_e32 v181, 1.0, v181
	v_rcp_f32_e32 v186, v181
	v_mul_f32_e32 v181, 0xbfb8aa3b, v159
	v_exp_f32_e32 v181, v181
	v_med3_f32 v2, v2, s92, v212
	v_med3_f32 v3, v3, s92, v212
	v_med3_f32 v4, v4, s92, v212
	v_med3_f32 v5, v5, s92, v212
	v_med3_f32 v6, v6, s92, v212
	v_med3_f32 v7, v7, s92, v212
	v_med3_f32 v8, v8, s92, v212
	v_med3_f32 v9, v9, s92, v212
	v_mul_f32_e32 v2, 0xbfb8aa3b, v2
	v_mul_f32_e32 v3, 0xbfb8aa3b, v3
	v_mul_f32_e32 v4, 0xbfb8aa3b, v4
	v_mul_f32_e32 v5, 0xbfb8aa3b, v5
	v_mul_f32_e32 v6, 0xbfb8aa3b, v6
	v_mul_f32_e32 v7, 0xbfb8aa3b, v7
	v_mul_f32_e32 v8, 0xbfb8aa3b, v8
	v_mul_f32_e32 v9, 0xbfb8aa3b, v9
	v_exp_f32_e32 v2, v2
	v_add_f32_e32 v160, 1.0, v160
	v_exp_f32_e32 v3, v3
	v_add_f32_e32 v161, 1.0, v161
	v_exp_f32_e32 v4, v4
	v_exp_f32_e32 v5, v5
	v_exp_f32_e32 v6, v6
	v_exp_f32_e32 v7, v7
	v_exp_f32_e32 v8, v8
	v_exp_f32_e32 v9, v9
	v_add_f32_e32 v181, 1.0, v181
	v_rcp_f32_e32 v160, v160
	v_rcp_f32_e32 v161, v161
	v_rcp_f32_e32 v187, v181
	v_pk_add_f32 v[2:3], v[2:3], 1.0 op_sel_hi:[1,0]
	v_pk_add_f32 v[4:5], v[4:5], 1.0 op_sel_hi:[1,0]
	v_pk_add_f32 v[6:7], v[6:7], 1.0 op_sel_hi:[1,0]
	v_pk_add_f32 v[8:9], v[8:9], 1.0 op_sel_hi:[1,0]
	v_pk_mul_f32 v[6:7], v[184:185], v[6:7]
	v_pk_mul_f32 v[8:9], v[186:187], v[8:9]
	v_pk_mul_f32 v[4:5], v[182:183], v[4:5]
	v_pk_mul_f32 v[2:3], v[160:161], v[2:3]
	s_mov_b64 s[4:5], 0

;     __device__ __forceinline__ bool operator()(f32x4 (&acc)[2][2][4][2], const Unit& u, int wr, int wc, int fr, int fq) const {
;     ...
;                 const u32x2 a = ca[bj];
;                 float e0[8] = {__builtin_amdgcn_cvt_f32_fp8((int)a.x, 0), __builtin_amdgcn_cvt_f32_fp8((int)a.x, 1), __builtin_amdgcn_cvt_f32_fp8((int)a.x, 2), __builtin_amdgcn_cvt_f32_fp8((int)a.x, 3),
;                                __builtin_amdgcn_cvt_f32_fp8((int)a.y, 0), __builtin_amdgcn_cvt_f32_fp8((int)a.y, 1), __builtin_amdgcn_cvt_f32_fp8((int)a.y, 2), __builtin_amdgcn_cvt_f32_fp8((int)a.y, 3)};
;                 float f[8];
;                 if (n < 3) { const u32x2 b = cb[bj];
;                     float e1[8] = {__builtin_amdgcn_cvt_f32_fp8((int)b.x, 0), __builtin_amdgcn_cvt_f32_fp8((int)b.x, 1), __builtin_amdgcn_cvt_f32_fp8((int)b.x, 2), __builtin_amdgcn_cvt_f32_fp8((int)b.x, 3),
;                                    __builtin_amdgcn_cvt_f32_fp8((int)b.y, 0), __builtin_amdgcn_cvt_f32_fp8((int)b.y, 1), __builtin_amdgcn_cvt_f32_fp8((int)b.y, 2), __builtin_amdgcn_cvt_f32_fp8((int)b.y, 3)};
; #pragma unroll
;                     for (int j = 0; j < 8; ++j) { const float x0 = fminf(fmaxf(e0[j], -30.f), 30.f), x1 = fminf(fmaxf(e1[j], -30.f), 30.f);
;                         f[j] = (1.f + __expf(-x1)) * __builtin_amdgcn_rcpf(1.f + __expf(-x0)); }
;                 } else {
; #pragma unroll
;                     for (int j = 0; j < 8; ++j) { const float x0 = fminf(fmaxf(e0[j], -30.f), 30.f); f[j] = __builtin_amdgcn_rcpf(1.f + __expf(-x0)); }
;                 }
;                 f32x4 v0 = acc[ai][bj][m][0], v1 = acc[ai][bj][m][1];
;                 v0[0] *= f[0]; v0[1] *= f[1]; v0[2] *= f[2]; v0[3] *= f[3]; v1[0] *= f[4]; v1[1] *= f[5]; v1[2] *= f[6]; v1[3] *= f[7];
;                 acc[ai][bj][m][0] = v0; acc[ai][bj][m][1] = v1;
.LBB0_1461:
	s_waitcnt vmcnt(0) lgkmcnt(0)
	s_nop 0
	v_cvt_f32_fp8_e32 v2, v174
	v_cvt_f32_fp8_sdwa v3, v174 src0_sel:BYTE_1
	v_cvt_f32_fp8_sdwa v4, v174 src0_sel:BYTE_2
	v_cvt_f32_fp8_sdwa v5, v174 src0_sel:BYTE_3
	v_cvt_f32_fp8_e32 v6, v175
	v_cvt_f32_fp8_sdwa v7, v175 src0_sel:BYTE_1
	v_cvt_f32_fp8_sdwa v8, v175 src0_sel:BYTE_2
	v_cvt_f32_fp8_sdwa v9, v175 src0_sel:BYTE_3
	s_mov_b64 s[4:5], -1
	s_and_b64 vcc, exec, s[58:59]
	v_med3_f32 v168, v2, s92, v212
	v_med3_f32 v165, v3, s92, v212
	v_med3_f32 v164, v4, s92, v212
	v_med3_f32 v161, v5, s92, v212
	v_med3_f32 v160, v6, s92, v212
	v_med3_f32 v159, v7, s92, v212
	v_med3_f32 v157, v8, s92, v212
	v_med3_f32 v156, v9, s92, v212
	s_cbranch_vccz .LBB0_1463
	v_mul_f32_e32 v169, 0xbfb8aa3b, v168
	v_exp_f32_e32 v169, v169
	v_cvt_f32_fp8_e32 v2, v170
	v_cvt_f32_fp8_sdwa v3, v170 src0_sel:BYTE_1
	v_cvt_f32_fp8_sdwa v4, v170 src0_sel:BYTE_2
	v_add_f32_e32 v169, 1.0, v169
	v_cvt_f32_fp8_sdwa v5, v170 src0_sel:BYTE_3
	v_rcp_f32_e32 v170, v169
	v_mul_f32_e32 v169, 0xbfb8aa3b, v165
	v_exp_f32_e32 v169, v169
	v_cvt_f32_fp8_e32 v6, v171
	v_cvt_f32_fp8_sdwa v7, v171 src0_sel:BYTE_1
	v_cvt_f32_fp8_sdwa v8, v171 src0_sel:BYTE_2
	v_add_f32_e32 v169, 1.0, v169
	v_cvt_f32_fp8_sdwa v9, v171 src0_sel:BYTE_3
	v_rcp_f32_e32 v171, v169
	v_mul_f32_e32 v169, 0xbfb8aa3b, v164
	v_exp_f32_e32 v169, v169
	s_nop 0
	v_add_f32_e32 v169, 1.0, v169
	v_rcp_f32_e32 v172, v169
	v_mul_f32_e32 v169, 0xbfb8aa3b, v161
	v_exp_f32_e32 v169, v169
	s_nop 0
	v_add_f32_e32 v169, 1.0, v169
	v_rcp_f32_e32 v173, v169
	v_mul_f32_e32 v169, 0xbfb8aa3b, v160
	v_exp_f32_e32 v169, v169
	v_med3_f32 v2, v2, s92, v212
	v_add_f32_e32 v169, 1.0, v169
	v_rcp_f32_e32 v174, v169
	v_mul_f32_e32 v169, 0xbfb8aa3b, v159
	v_exp_f32_e32 v169, v169
	v_med3_f32 v3, v3, s92, v212
	v_med3_f32 v4, v4, s92, v212
	v_med3_f32 v5, v5, s92, v212
	v_add_f32_e32 v169, 1.0, v169
	v_rcp_f32_e32 v175, v169
	v_mul_f32_e32 v169, 0xbfb8aa3b, v157
	v_exp_f32_e32 v169, v169
	v_med3_f32 v6, v6, s92, v212
	v_med3_f32 v7, v7, s92, v212
	v_med3_f32 v8, v8, s92, v212
	v_add_f32_e32 v169, 1.0, v169
	v_rcp_f32_e32 v180, v169
	v_mul_f32_e32 v169, 0xbfb8aa3b, v156
	v_exp_f32_e32 v169, v169
	v_med3_f32 v9, v9, s92, v212
	v_mul_f32_e32 v2, 0xbfb8aa3b, v2
	v_mul_f32_e32 v3, 0xbfb8aa3b, v3
	v_mul_f32_e32 v4, 0xbfb8aa3b, v4
	v_mul_f32_e32 v5, 0xbfb8aa3b, v5
	v_mul_f32_e32 v6, 0xbfb8aa3b, v6
	v_mul_f32_e32 v7, 0xbfb8aa3b, v7
	v_mul_f32_e32 v8, 0xbfb8aa3b, v8
	v_mul_f32_e32 v9, 0xbfb8aa3b, v9
	v_exp_f32_e32 v2, v2
	v_exp_f32_e32 v3, v3
	v_exp_f32_e32 v4, v4
	v_exp_f32_e32 v5, v5
	v_exp_f32_e32 v6, v6
	v_exp_f32_e32 v7, v7
	v_exp_f32_e32 v8, v8
	v_exp_f32_e32 v9, v9
	v_add_f32_e32 v169, 1.0, v169
	v_rcp_f32_e32 v181, v169
	v_pk_add_f32 v[2:3], v[2:3], 1.0 op_sel_hi:[1,0]
	v_pk_add_f32 v[4:5], v[4:5], 1.0 op_sel_hi:[1,0]
	v_pk_add_f32 v[6:7], v[6:7], 1.0 op_sel_hi:[1,0]
	v_pk_add_f32 v[8:9], v[8:9], 1.0 op_sel_hi:[1,0]
	v_pk_mul_f32 v[6:7], v[174:175], v[6:7]
	v_pk_mul_f32 v[8:9], v[180:181], v[8:9]
	v_pk_mul_f32 v[4:5], v[172:173], v[4:5]
	v_pk_mul_f32 v[2:3], v[170:171], v[2:3]
	s_mov_b64 s[4:5], 0

;     __device__ __forceinline__ bool operator()(f32x4 (&acc)[2][2][4][2], const Unit& u, int wr, int wc, int fr, int fq) const {
;     ...
;                 const u32x2 a = ca[bj];
;                 float e0[8] = {__builtin_amdgcn_cvt_f32_fp8((int)a.x, 0), __builtin_amdgcn_cvt_f32_fp8((int)a.x, 1), __builtin_amdgcn_cvt_f32_fp8((int)a.x, 2), __builtin_amdgcn_cvt_f32_fp8((int)a.x, 3),
;                                __builtin_amdgcn_cvt_f32_fp8((int)a.y, 0), __builtin_amdgcn_cvt_f32_fp8((int)a.y, 1), __builtin_amdgcn_cvt_f32_fp8((int)a.y, 2), __builtin_amdgcn_cvt_f32_fp8((int)a.y, 3)};
;                 float f[8];
;                 if (n < 3) { const u32x2 b = cb[bj];
;                     float e1[8] = {__builtin_amdgcn_cvt_f32_fp8((int)b.x, 0), __builtin_amdgcn_cvt_f32_fp8((int)b.x, 1), __builtin_amdgcn_cvt_f32_fp8((int)b.x, 2), __builtin_amdgcn_cvt_f32_fp8((int)b.x, 3),
;                                    __builtin_amdgcn_cvt_f32_fp8((int)b.y, 0), __builtin_amdgcn_cvt_f32_fp8((int)b.y, 1), __builtin_amdgcn_cvt_f32_fp8((int)b.y, 2), __builtin_amdgcn_cvt_f32_fp8((int)b.y, 3)};
; #pragma unroll
;                     for (int j = 0; j < 8; ++j) { const float x0 = fminf(fmaxf(e0[j], -30.f), 30.f), x1 = fminf(fmaxf(e1[j], -30.f), 30.f);
;                         f[j] = (1.f + __expf(-x1)) * __builtin_amdgcn_rcpf(1.f + __expf(-x0)); }
;                 } else {
; #pragma unroll
;                     for (int j = 0; j < 8; ++j) { const float x0 = fminf(fmaxf(e0[j], -30.f), 30.f); f[j] = __builtin_amdgcn_rcpf(1.f + __expf(-x0)); }
;                 }
;                 f32x4 v0 = acc[ai][bj][m][0], v1 = acc[ai][bj][m][1];
;                 v0[0] *= f[0]; v0[1] *= f[1]; v0[2] *= f[2]; v0[3] *= f[3]; v1[0] *= f[4]; v1[1] *= f[5]; v1[2] *= f[6]; v1[3] *= f[7];
;                 acc[ai][bj][m][0] = v0; acc[ai][bj][m][1] = v1;
.LBB0_1467:
	s_nop 1
	v_cvt_f32_fp8_e32 v2, v166
	v_cvt_f32_fp8_sdwa v3, v166 src0_sel:BYTE_1
	v_cvt_f32_fp8_sdwa v4, v166 src0_sel:BYTE_2
	v_cvt_f32_fp8_sdwa v5, v166 src0_sel:BYTE_3
	v_cvt_f32_fp8_e32 v6, v167
	v_cvt_f32_fp8_sdwa v7, v167 src0_sel:BYTE_1
	v_cvt_f32_fp8_sdwa v8, v167 src0_sel:BYTE_2
	v_cvt_f32_fp8_sdwa v9, v167 src0_sel:BYTE_3
	s_mov_b64 s[4:5], -1
	s_and_b64 vcc, exec, s[58:59]
	v_med3_f32 v165, v2, s92, v212
	v_med3_f32 v164, v3, s92, v212
	v_med3_f32 v161, v4, s92, v212
	v_med3_f32 v160, v5, s92, v212
	v_med3_f32 v159, v6, s92, v212
	v_med3_f32 v158, v7, s92, v212
	v_med3_f32 v157, v8, s92, v212
	v_med3_f32 v156, v9, s92, v212
	s_cbranch_vccz .LBB0_1469
	v_cvt_f32_fp8_e32 v2, v162
	v_cvt_f32_fp8_sdwa v3, v162 src0_sel:BYTE_1
	v_cvt_f32_fp8_sdwa v4, v162 src0_sel:BYTE_2
	v_cvt_f32_fp8_sdwa v5, v162 src0_sel:BYTE_3
	v_cvt_f32_fp8_e32 v6, v163
	v_cvt_f32_fp8_sdwa v7, v163 src0_sel:BYTE_1
	v_cvt_f32_fp8_sdwa v8, v163 src0_sel:BYTE_2
	v_cvt_f32_fp8_sdwa v9, v163 src0_sel:BYTE_3
	v_mul_f32_e32 v162, 0xbfb8aa3b, v165
	v_mul_f32_e32 v163, 0xbfb8aa3b, v164
	v_mul_f32_e32 v166, 0xbfb8aa3b, v161
	v_mul_f32_e32 v167, 0xbfb8aa3b, v160
	v_mul_f32_e32 v168, 0xbfb8aa3b, v159
	v_mul_f32_e32 v169, 0xbfb8aa3b, v158
	v_mul_f32_e32 v170, 0xbfb8aa3b, v157
	v_mul_f32_e32 v171, 0xbfb8aa3b, v156
	v_exp_f32_e32 v162, v162
	v_exp_f32_e32 v163, v163
	v_exp_f32_e32 v166, v166
	v_exp_f32_e32 v167, v167
	v_exp_f32_e32 v168, v168
	v_exp_f32_e32 v169, v169
	v_exp_f32_e32 v170, v170
	v_exp_f32_e32 v171, v171
	v_med3_f32 v2, v2, s92, v212
	v_med3_f32 v3, v3, s92, v212
	v_med3_f32 v4, v4, s92, v212
	v_med3_f32 v5, v5, s92, v212
	v_med3_f32 v6, v6, s92, v212
	v_med3_f32 v7, v7, s92, v212
	v_med3_f32 v8, v8, s92, v212
	v_med3_f32 v9, v9, s92, v212
	v_mul_f32_e32 v2, 0xbfb8aa3b, v2
	v_mul_f32_e32 v3, 0xbfb8aa3b, v3
	v_mul_f32_e32 v4, 0xbfb8aa3b, v4
	v_mul_f32_e32 v5, 0xbfb8aa3b, v5
	v_mul_f32_e32 v6, 0xbfb8aa3b, v6
	v_mul_f32_e32 v7, 0xbfb8aa3b, v7
	v_mul_f32_e32 v8, 0xbfb8aa3b, v8
	v_mul_f32_e32 v9, 0xbfb8aa3b, v9
	v_exp_f32_e32 v2, v2
	v_add_f32_e32 v162, 1.0, v162
	v_exp_f32_e32 v3, v3
	v_add_f32_e32 v163, 1.0, v163
	v_exp_f32_e32 v4, v4
	v_add_f32_e32 v166, 1.0, v166
	v_exp_f32_e32 v5, v5
	v_add_f32_e32 v167, 1.0, v167
	v_exp_f32_e32 v6, v6
	v_add_f32_e32 v168, 1.0, v168
	v_exp_f32_e32 v7, v7
	v_add_f32_e32 v169, 1.0, v169
	v_exp_f32_e32 v8, v8
	v_add_f32_e32 v170, 1.0, v170
	v_exp_f32_e32 v9, v9
	v_add_f32_e32 v171, 1.0, v171
	v_rcp_f32_e32 v162, v162
	v_rcp_f32_e32 v163, v163
	v_rcp_f32_e32 v166, v166
	v_rcp_f32_e32 v167, v167
	v_rcp_f32_e32 v168, v168
	v_rcp_f32_e32 v169, v169
	v_rcp_f32_e32 v170, v170
	v_rcp_f32_e32 v171, v171
	v_pk_add_f32 v[2:3], v[2:3], 1.0 op_sel_hi:[1,0]
	v_pk_add_f32 v[4:5], v[4:5], 1.0 op_sel_hi:[1,0]
	v_pk_add_f32 v[6:7], v[6:7], 1.0 op_sel_hi:[1,0]
	v_pk_add_f32 v[8:9], v[8:9], 1.0 op_sel_hi:[1,0]
	v_pk_mul_f32 v[6:7], v[168:169], v[6:7]
	v_pk_mul_f32 v[8:9], v[170:171], v[8:9]
	v_pk_mul_f32 v[4:5], v[166:167], v[4:5]
	v_pk_mul_f32 v[2:3], v[162:163], v[2:3]
	s_mov_b64 s[4:5], 0
